# pool tile loop fully unrolled: all 16 gate loads up front, W frags double-buffered, scale ring
# speedup vs baseline: 1.0007x; 1.0007x over previous
.LBB0_557:
	v_mov_b64_e32 v[34:35], s[28:29]
	v_lshl_or_b32 v104, s8, 8, v140
	v_mad_i64_i32 v[34:35], s[10:11], v32, s18, v[34:35]
	v_ashrrev_i32_e32 v105, 31, v104
	v_lshl_add_u64 v[106:107], v[34:35], 0, s[4:5]
	v_lshlrev_b64 v[34:35], 1, v[104:105]
	v_or_b32_e32 v108, 16, v104
	v_lshl_add_u64 v[36:37], v[106:107], 0, v[34:35]
	v_ashrrev_i32_e32 v109, 31, v108
	v_or_b32_e32 v110, 32, v104
	v_or_b32_e32 v112, 48, v104
	s_waitcnt lgkmcnt(0)
	s_barrier
	v_mov_b32_e32 v170, v36
	v_mov_b32_e32 v171, v37
	v_lshlrev_b64 v[132:133], 12, v[32:33]
	v_lshl_add_u64 v[130:131], v[104:105], 2, s[60:61]
	v_lshl_add_u64 v[132:133], s[30:31], 0, v[132:133]
	v_mov_b32_e32 v64, v143
	v_add_u32_e32 v103, 0x10800, v143
	v_lshl_add_u64 v[132:133], v[104:105], 1, v[132:133]
	ds_read_b128 v[174:177], v64
	ds_read_b128 v[178:181], v64 offset:64
	ds_read_b128 v[182:185], v64 offset:128
	ds_read_b128 v[186:189], v64 offset:192
	ds_read_b128 v[190:193], v64 offset:256
	ds_read_b128 v[194:197], v64 offset:320
	ds_read_b128 v[198:201], v64 offset:384
	ds_read_b128 v[202:205], v64 offset:448
	global_load_dwordx2 v[32:33], v[170:171], off
	global_load_dwordx2 v[34:35], v[170:171], off offset:32
	global_load_dwordx2 v[36:37], v[170:171], off offset:64
	global_load_dwordx2 v[38:39], v[170:171], off offset:96
	global_load_dwordx2 v[40:41], v[170:171], off offset:128
	global_load_dwordx2 v[42:43], v[170:171], off offset:160
	global_load_dwordx2 v[44:45], v[170:171], off offset:192
	global_load_dwordx2 v[46:47], v[170:171], off offset:224
	global_load_dwordx2 v[48:49], v[170:171], off offset:256
	global_load_dwordx2 v[50:51], v[170:171], off offset:288
	global_load_dwordx2 v[52:53], v[170:171], off offset:320
	global_load_dwordx2 v[54:55], v[170:171], off offset:352
	global_load_dwordx2 v[56:57], v[170:171], off offset:384
	global_load_dwordx2 v[58:59], v[170:171], off offset:416
	global_load_dwordx2 v[60:61], v[170:171], off offset:448
	global_load_dwordx2 v[62:63], v[170:171], off offset:480
	global_load_dwordx4 v[118:121], v[130:131], off
	global_load_dwordx4 v[122:125], v[130:131], off offset:64
	global_load_dwordx4 v[126:129], v[130:131], off offset:128
	s_waitcnt lgkmcnt(0)
	ds_read_b128 v[206:209], v64 offset:8448
	ds_read_b128 v[210:213], v64 offset:8512
	ds_read_b128 v[214:217], v64 offset:8576
	ds_read_b128 v[218:221], v64 offset:8640
	ds_read_b128 v[222:225], v64 offset:8704
	ds_read_b128 v[226:229], v64 offset:8768
	ds_read_b128 v[230:233], v64 offset:8832
	ds_read_b128 v[234:237], v64 offset:8896
	s_waitcnt vmcnt(26)
	v_mfma_f32_16x16x32_bf16 v[162:165], v[174:177], v[0:3], 0
	s_waitcnt vmcnt(25)
	v_mfma_f32_16x16x32_bf16 v[162:165], v[178:181], v[4:7], v[162:165]
	s_waitcnt vmcnt(24)
	v_mfma_f32_16x16x32_bf16 v[162:165], v[182:185], v[8:11], v[162:165]
	s_waitcnt vmcnt(23)
	v_mfma_f32_16x16x32_bf16 v[162:165], v[186:189], v[12:15], v[162:165]
	s_waitcnt vmcnt(22)
	v_mfma_f32_16x16x32_bf16 v[162:165], v[190:193], v[16:19], v[162:165]
	s_waitcnt vmcnt(21)
	v_mfma_f32_16x16x32_bf16 v[162:165], v[194:197], v[20:23], v[162:165]
	s_waitcnt vmcnt(20)
	v_mfma_f32_16x16x32_bf16 v[162:165], v[198:201], v[24:27], v[162:165]
	s_waitcnt vmcnt(19)
	v_mfma_f32_16x16x32_bf16 v[162:165], v[202:205], v[28:31], v[162:165]
	s_waitcnt vmcnt(18)
	v_lshlrev_b32_e32 v170, 16, v32
	v_and_b32_e32 v171, 0xffff0000, v32
	v_mul_f32_e32 v166, 0xbfb8aa3b, v170
	v_exp_f32_e32 v166, v166
	s_nop 0
	v_add_f32_e32 v166, 1.0, v166
	v_rcp_f32_e32 v172, v166
	v_mul_f32_e32 v166, 0xbfb8aa3b, v171
	v_exp_f32_e32 v166, v166
	s_nop 0
	v_add_f32_e32 v166, 1.0, v166
	v_rcp_f32_e32 v173, v166
	s_waitcnt vmcnt(2)
	v_pk_mul_f32 v[118:119], v[118:119], v[162:163]
	v_pk_mul_f32 v[120:121], v[120:121], v[164:165]
	v_pk_mul_f32 v[172:173], v[172:173], v[170:171]
	s_nop 0
	v_pk_mul_f32 v[118:119], v[172:173], v[118:119]
	s_nop 0
	v_cvt_pk_bf16_f32 v166, v118, v119
	v_lshlrev_b32_e32 v170, 16, v33
	v_and_b32_e32 v171, 0xffff0000, v33
	v_mul_f32_e32 v167, 0xbfb8aa3b, v170
	v_exp_f32_e32 v167, v167
	s_nop 0
	v_add_f32_e32 v167, 1.0, v167
	v_rcp_f32_e32 v172, v167
	v_mul_f32_e32 v167, 0xbfb8aa3b, v171
	v_exp_f32_e32 v167, v167
	s_nop 0
	v_add_f32_e32 v167, 1.0, v167
	v_rcp_f32_e32 v173, v167
	s_nop 1
	v_pk_mul_f32 v[172:173], v[172:173], v[170:171]
	s_nop 0
	v_pk_mul_f32 v[120:121], v[172:173], v[120:121]
	s_nop 0
	v_cvt_pk_bf16_f32 v167, v120, v121
	s_nop 0
	global_store_dwordx2 v[132:133], v[166:167], off offset:2048
	global_load_dwordx4 v[118:121], v[130:131], off offset:192
	s_waitcnt lgkmcnt(0)
	ds_read_b128 v[174:177], v64 offset:16896
	ds_read_b128 v[178:181], v64 offset:16960
	ds_read_b128 v[182:185], v64 offset:17024
	ds_read_b128 v[186:189], v64 offset:17088
	ds_read_b128 v[190:193], v64 offset:17152
	ds_read_b128 v[194:197], v64 offset:17216
	ds_read_b128 v[198:201], v64 offset:17280
	ds_read_b128 v[202:205], v64 offset:17344
	v_mfma_f32_16x16x32_bf16 v[162:165], v[206:209], v[0:3], 0
	v_mfma_f32_16x16x32_bf16 v[162:165], v[210:213], v[4:7], v[162:165]
	v_mfma_f32_16x16x32_bf16 v[162:165], v[214:217], v[8:11], v[162:165]
	v_mfma_f32_16x16x32_bf16 v[162:165], v[218:221], v[12:15], v[162:165]
	v_mfma_f32_16x16x32_bf16 v[162:165], v[222:225], v[16:19], v[162:165]
	v_mfma_f32_16x16x32_bf16 v[162:165], v[226:229], v[20:23], v[162:165]
	v_mfma_f32_16x16x32_bf16 v[162:165], v[230:233], v[24:27], v[162:165]
	v_mfma_f32_16x16x32_bf16 v[162:165], v[234:237], v[28:31], v[162:165]
	s_waitcnt vmcnt(19)
	v_lshlrev_b32_e32 v170, 16, v34
	v_and_b32_e32 v171, 0xffff0000, v34
	v_mul_f32_e32 v166, 0xbfb8aa3b, v170
	v_exp_f32_e32 v166, v166
	s_nop 0
	v_add_f32_e32 v166, 1.0, v166
	v_rcp_f32_e32 v172, v166
	v_mul_f32_e32 v166, 0xbfb8aa3b, v171
	v_exp_f32_e32 v166, v166
	s_nop 0
	v_add_f32_e32 v166, 1.0, v166
	v_rcp_f32_e32 v173, v166
	s_waitcnt vmcnt(3)
	v_pk_mul_f32 v[122:123], v[122:123], v[162:163]
	v_pk_mul_f32 v[124:125], v[124:125], v[164:165]
	v_pk_mul_f32 v[172:173], v[172:173], v[170:171]
	s_nop 0
	v_pk_mul_f32 v[122:123], v[172:173], v[122:123]
	s_nop 0
	v_cvt_pk_bf16_f32 v166, v122, v123
	v_lshlrev_b32_e32 v170, 16, v35
	v_and_b32_e32 v171, 0xffff0000, v35
	v_mul_f32_e32 v167, 0xbfb8aa3b, v170
	v_exp_f32_e32 v167, v167
	s_nop 0
	v_add_f32_e32 v167, 1.0, v167
	v_rcp_f32_e32 v172, v167
	v_mul_f32_e32 v167, 0xbfb8aa3b, v171
	v_exp_f32_e32 v167, v167
	s_nop 0
	v_add_f32_e32 v167, 1.0, v167
	v_rcp_f32_e32 v173, v167
	s_nop 1
	v_pk_mul_f32 v[172:173], v[172:173], v[170:171]
	s_nop 0
	v_pk_mul_f32 v[124:125], v[172:173], v[124:125]
	s_nop 0
	v_cvt_pk_bf16_f32 v167, v124, v125
	s_nop 0
	global_store_dwordx2 v[132:133], v[166:167], off offset:2080
	global_load_dwordx4 v[122:125], v[130:131], off offset:256
	s_waitcnt lgkmcnt(0)
	ds_read_b128 v[206:209], v64 offset:25344
	ds_read_b128 v[210:213], v64 offset:25408
	ds_read_b128 v[214:217], v64 offset:25472
	ds_read_b128 v[218:221], v64 offset:25536
	ds_read_b128 v[222:225], v64 offset:25600
	ds_read_b128 v[226:229], v64 offset:25664
	ds_read_b128 v[230:233], v64 offset:25728
	ds_read_b128 v[234:237], v64 offset:25792
	v_mfma_f32_16x16x32_bf16 v[162:165], v[174:177], v[0:3], 0
	v_mfma_f32_16x16x32_bf16 v[162:165], v[178:181], v[4:7], v[162:165]
	v_mfma_f32_16x16x32_bf16 v[162:165], v[182:185], v[8:11], v[162:165]
	v_mfma_f32_16x16x32_bf16 v[162:165], v[186:189], v[12:15], v[162:165]
	v_mfma_f32_16x16x32_bf16 v[162:165], v[190:193], v[16:19], v[162:165]
	v_mfma_f32_16x16x32_bf16 v[162:165], v[194:197], v[20:23], v[162:165]
	v_mfma_f32_16x16x32_bf16 v[162:165], v[198:201], v[24:27], v[162:165]
	v_mfma_f32_16x16x32_bf16 v[162:165], v[202:205], v[28:31], v[162:165]
	s_waitcnt vmcnt(20)
	v_lshlrev_b32_e32 v170, 16, v36
	v_and_b32_e32 v171, 0xffff0000, v36
	v_mul_f32_e32 v166, 0xbfb8aa3b, v170
	v_exp_f32_e32 v166, v166
	s_nop 0
	v_add_f32_e32 v166, 1.0, v166
	v_rcp_f32_e32 v172, v166
	v_mul_f32_e32 v166, 0xbfb8aa3b, v171
	v_exp_f32_e32 v166, v166
	s_nop 0
	v_add_f32_e32 v166, 1.0, v166
	v_rcp_f32_e32 v173, v166
	s_waitcnt vmcnt(4)
	v_pk_mul_f32 v[126:127], v[126:127], v[162:163]
	v_pk_mul_f32 v[128:129], v[128:129], v[164:165]
	v_pk_mul_f32 v[172:173], v[172:173], v[170:171]
	s_nop 0
	v_pk_mul_f32 v[126:127], v[172:173], v[126:127]
	s_nop 0
	v_cvt_pk_bf16_f32 v166, v126, v127
	v_lshlrev_b32_e32 v170, 16, v37
	v_and_b32_e32 v171, 0xffff0000, v37
	v_mul_f32_e32 v167, 0xbfb8aa3b, v170
	v_exp_f32_e32 v167, v167
	s_nop 0
	v_add_f32_e32 v167, 1.0, v167
	v_rcp_f32_e32 v172, v167
	v_mul_f32_e32 v167, 0xbfb8aa3b, v171
	v_exp_f32_e32 v167, v167
	s_nop 0
	v_add_f32_e32 v167, 1.0, v167
	v_rcp_f32_e32 v173, v167
	s_nop 1
	v_pk_mul_f32 v[172:173], v[172:173], v[170:171]
	s_nop 0
	v_pk_mul_f32 v[128:129], v[172:173], v[128:129]
	s_nop 0
	v_cvt_pk_bf16_f32 v167, v128, v129
	s_nop 0
	global_store_dwordx2 v[132:133], v[166:167], off offset:2112
	global_load_dwordx4 v[126:129], v[130:131], off offset:320
	s_waitcnt lgkmcnt(0)
	ds_read_b128 v[174:177], v64 offset:33792
	ds_read_b128 v[178:181], v64 offset:33856
	ds_read_b128 v[182:185], v64 offset:33920
	ds_read_b128 v[186:189], v64 offset:33984
	ds_read_b128 v[190:193], v64 offset:34048
	ds_read_b128 v[194:197], v64 offset:34112
	ds_read_b128 v[198:201], v64 offset:34176
	ds_read_b128 v[202:205], v64 offset:34240
	v_mfma_f32_16x16x32_bf16 v[162:165], v[206:209], v[0:3], 0
	v_mfma_f32_16x16x32_bf16 v[162:165], v[210:213], v[4:7], v[162:165]
	v_mfma_f32_16x16x32_bf16 v[162:165], v[214:217], v[8:11], v[162:165]
	v_mfma_f32_16x16x32_bf16 v[162:165], v[218:221], v[12:15], v[162:165]
	v_mfma_f32_16x16x32_bf16 v[162:165], v[222:225], v[16:19], v[162:165]
	v_mfma_f32_16x16x32_bf16 v[162:165], v[226:229], v[20:23], v[162:165]
	v_mfma_f32_16x16x32_bf16 v[162:165], v[230:233], v[24:27], v[162:165]
	v_mfma_f32_16x16x32_bf16 v[162:165], v[234:237], v[28:31], v[162:165]
	s_waitcnt vmcnt(21)
	v_lshlrev_b32_e32 v170, 16, v38
	v_and_b32_e32 v171, 0xffff0000, v38
	v_mul_f32_e32 v166, 0xbfb8aa3b, v170
	v_exp_f32_e32 v166, v166
	s_nop 0
	v_add_f32_e32 v166, 1.0, v166
	v_rcp_f32_e32 v172, v166
	v_mul_f32_e32 v166, 0xbfb8aa3b, v171
	v_exp_f32_e32 v166, v166
	s_nop 0
	v_add_f32_e32 v166, 1.0, v166
	v_rcp_f32_e32 v173, v166
	s_waitcnt vmcnt(4)
	v_pk_mul_f32 v[118:119], v[118:119], v[162:163]
	v_pk_mul_f32 v[120:121], v[120:121], v[164:165]
	v_pk_mul_f32 v[172:173], v[172:173], v[170:171]
	s_nop 0
	v_pk_mul_f32 v[118:119], v[172:173], v[118:119]
	s_nop 0
	v_cvt_pk_bf16_f32 v166, v118, v119
	v_lshlrev_b32_e32 v170, 16, v39
	v_and_b32_e32 v171, 0xffff0000, v39
	v_mul_f32_e32 v167, 0xbfb8aa3b, v170
	v_exp_f32_e32 v167, v167
	s_nop 0
	v_add_f32_e32 v167, 1.0, v167
	v_rcp_f32_e32 v172, v167
	v_mul_f32_e32 v167, 0xbfb8aa3b, v171
	v_exp_f32_e32 v167, v167
	s_nop 0
	v_add_f32_e32 v167, 1.0, v167
	v_rcp_f32_e32 v173, v167
	s_nop 1
	v_pk_mul_f32 v[172:173], v[172:173], v[170:171]
	s_nop 0
	v_pk_mul_f32 v[120:121], v[172:173], v[120:121]
	s_nop 0
	v_cvt_pk_bf16_f32 v167, v120, v121
	s_nop 0
	global_store_dwordx2 v[132:133], v[166:167], off offset:2144
	global_load_dwordx4 v[118:121], v[130:131], off offset:384
	s_waitcnt lgkmcnt(0)
	ds_read_b128 v[206:209], v64 offset:42240
	ds_read_b128 v[210:213], v64 offset:42304
	ds_read_b128 v[214:217], v64 offset:42368
	ds_read_b128 v[218:221], v64 offset:42432
	ds_read_b128 v[222:225], v64 offset:42496
	ds_read_b128 v[226:229], v64 offset:42560
	ds_read_b128 v[230:233], v64 offset:42624
	ds_read_b128 v[234:237], v64 offset:42688
	v_mfma_f32_16x16x32_bf16 v[162:165], v[174:177], v[0:3], 0
	v_mfma_f32_16x16x32_bf16 v[162:165], v[178:181], v[4:7], v[162:165]
	v_mfma_f32_16x16x32_bf16 v[162:165], v[182:185], v[8:11], v[162:165]
	v_mfma_f32_16x16x32_bf16 v[162:165], v[186:189], v[12:15], v[162:165]
	v_mfma_f32_16x16x32_bf16 v[162:165], v[190:193], v[16:19], v[162:165]
	v_mfma_f32_16x16x32_bf16 v[162:165], v[194:197], v[20:23], v[162:165]
	v_mfma_f32_16x16x32_bf16 v[162:165], v[198:201], v[24:27], v[162:165]
	v_mfma_f32_16x16x32_bf16 v[162:165], v[202:205], v[28:31], v[162:165]
	s_waitcnt vmcnt(22)
	v_lshlrev_b32_e32 v170, 16, v40
	v_and_b32_e32 v171, 0xffff0000, v40
	v_mul_f32_e32 v166, 0xbfb8aa3b, v170
	v_exp_f32_e32 v166, v166
	s_nop 0
	v_add_f32_e32 v166, 1.0, v166
	v_rcp_f32_e32 v172, v166
	v_mul_f32_e32 v166, 0xbfb8aa3b, v171
	v_exp_f32_e32 v166, v166
	s_nop 0
	v_add_f32_e32 v166, 1.0, v166
	v_rcp_f32_e32 v173, v166
	s_waitcnt vmcnt(4)
	v_pk_mul_f32 v[122:123], v[122:123], v[162:163]
	v_pk_mul_f32 v[124:125], v[124:125], v[164:165]
	v_pk_mul_f32 v[172:173], v[172:173], v[170:171]
	s_nop 0
	v_pk_mul_f32 v[122:123], v[172:173], v[122:123]
	s_nop 0
	v_cvt_pk_bf16_f32 v166, v122, v123
	v_lshlrev_b32_e32 v170, 16, v41
	v_and_b32_e32 v171, 0xffff0000, v41
	v_mul_f32_e32 v167, 0xbfb8aa3b, v170
	v_exp_f32_e32 v167, v167
	s_nop 0
	v_add_f32_e32 v167, 1.0, v167
	v_rcp_f32_e32 v172, v167
	v_mul_f32_e32 v167, 0xbfb8aa3b, v171
	v_exp_f32_e32 v167, v167
	s_nop 0
	v_add_f32_e32 v167, 1.0, v167
	v_rcp_f32_e32 v173, v167
	s_nop 1
	v_pk_mul_f32 v[172:173], v[172:173], v[170:171]
	s_nop 0
	v_pk_mul_f32 v[124:125], v[172:173], v[124:125]
	s_nop 0
	v_cvt_pk_bf16_f32 v167, v124, v125
	s_nop 0
	global_store_dwordx2 v[132:133], v[166:167], off offset:2176
	global_load_dwordx4 v[122:125], v[130:131], off offset:448
	s_waitcnt lgkmcnt(0)
	ds_read_b128 v[174:177], v64 offset:50688
	ds_read_b128 v[178:181], v64 offset:50752
	ds_read_b128 v[182:185], v64 offset:50816
	ds_read_b128 v[186:189], v64 offset:50880
	ds_read_b128 v[190:193], v64 offset:50944
	ds_read_b128 v[194:197], v64 offset:51008
	ds_read_b128 v[198:201], v64 offset:51072
	ds_read_b128 v[202:205], v64 offset:51136
	v_mfma_f32_16x16x32_bf16 v[162:165], v[206:209], v[0:3], 0
	v_mfma_f32_16x16x32_bf16 v[162:165], v[210:213], v[4:7], v[162:165]
	v_mfma_f32_16x16x32_bf16 v[162:165], v[214:217], v[8:11], v[162:165]
	v_mfma_f32_16x16x32_bf16 v[162:165], v[218:221], v[12:15], v[162:165]
	v_mfma_f32_16x16x32_bf16 v[162:165], v[222:225], v[16:19], v[162:165]
	v_mfma_f32_16x16x32_bf16 v[162:165], v[226:229], v[20:23], v[162:165]
	v_mfma_f32_16x16x32_bf16 v[162:165], v[230:233], v[24:27], v[162:165]
	v_mfma_f32_16x16x32_bf16 v[162:165], v[234:237], v[28:31], v[162:165]
	s_waitcnt vmcnt(23)
	v_lshlrev_b32_e32 v170, 16, v42
	v_and_b32_e32 v171, 0xffff0000, v42
	v_mul_f32_e32 v166, 0xbfb8aa3b, v170
	v_exp_f32_e32 v166, v166
	s_nop 0
	v_add_f32_e32 v166, 1.0, v166
	v_rcp_f32_e32 v172, v166
	v_mul_f32_e32 v166, 0xbfb8aa3b, v171
	v_exp_f32_e32 v166, v166
	s_nop 0
	v_add_f32_e32 v166, 1.0, v166
	v_rcp_f32_e32 v173, v166
	s_waitcnt vmcnt(4)
	v_pk_mul_f32 v[126:127], v[126:127], v[162:163]
	v_pk_mul_f32 v[128:129], v[128:129], v[164:165]
	v_pk_mul_f32 v[172:173], v[172:173], v[170:171]
	s_nop 0
	v_pk_mul_f32 v[126:127], v[172:173], v[126:127]
	s_nop 0
	v_cvt_pk_bf16_f32 v166, v126, v127
	v_lshlrev_b32_e32 v170, 16, v43
	v_and_b32_e32 v171, 0xffff0000, v43
	v_mul_f32_e32 v167, 0xbfb8aa3b, v170
	v_exp_f32_e32 v167, v167
	s_nop 0
	v_add_f32_e32 v167, 1.0, v167
	v_rcp_f32_e32 v172, v167
	v_mul_f32_e32 v167, 0xbfb8aa3b, v171
	v_exp_f32_e32 v167, v167
	s_nop 0
	v_add_f32_e32 v167, 1.0, v167
	v_rcp_f32_e32 v173, v167
	s_nop 1
	v_pk_mul_f32 v[172:173], v[172:173], v[170:171]
	s_nop 0
	v_pk_mul_f32 v[128:129], v[172:173], v[128:129]
	s_nop 0
	v_cvt_pk_bf16_f32 v167, v128, v129
	s_nop 0
	global_store_dwordx2 v[132:133], v[166:167], off offset:2208
	global_load_dwordx4 v[126:129], v[130:131], off offset:512
	s_waitcnt lgkmcnt(0)
	ds_read_b128 v[206:209], v64 offset:59136
	ds_read_b128 v[210:213], v64 offset:59200
	ds_read_b128 v[214:217], v64 offset:59264
	ds_read_b128 v[218:221], v64 offset:59328
	ds_read_b128 v[222:225], v64 offset:59392
	ds_read_b128 v[226:229], v64 offset:59456
	ds_read_b128 v[230:233], v64 offset:59520
	ds_read_b128 v[234:237], v64 offset:59584
	v_mfma_f32_16x16x32_bf16 v[162:165], v[174:177], v[0:3], 0
	v_mfma_f32_16x16x32_bf16 v[162:165], v[178:181], v[4:7], v[162:165]
	v_mfma_f32_16x16x32_bf16 v[162:165], v[182:185], v[8:11], v[162:165]
	v_mfma_f32_16x16x32_bf16 v[162:165], v[186:189], v[12:15], v[162:165]
	v_mfma_f32_16x16x32_bf16 v[162:165], v[190:193], v[16:19], v[162:165]
	v_mfma_f32_16x16x32_bf16 v[162:165], v[194:197], v[20:23], v[162:165]
	v_mfma_f32_16x16x32_bf16 v[162:165], v[198:201], v[24:27], v[162:165]
	v_mfma_f32_16x16x32_bf16 v[162:165], v[202:205], v[28:31], v[162:165]
	s_waitcnt vmcnt(24)
	v_lshlrev_b32_e32 v170, 16, v44
	v_and_b32_e32 v171, 0xffff0000, v44
	v_mul_f32_e32 v166, 0xbfb8aa3b, v170
	v_exp_f32_e32 v166, v166
	s_nop 0
	v_add_f32_e32 v166, 1.0, v166
	v_rcp_f32_e32 v172, v166
	v_mul_f32_e32 v166, 0xbfb8aa3b, v171
	v_exp_f32_e32 v166, v166
	s_nop 0
	v_add_f32_e32 v166, 1.0, v166
	v_rcp_f32_e32 v173, v166
	s_waitcnt vmcnt(4)
	v_pk_mul_f32 v[118:119], v[118:119], v[162:163]
	v_pk_mul_f32 v[120:121], v[120:121], v[164:165]
	v_pk_mul_f32 v[172:173], v[172:173], v[170:171]
	s_nop 0
	v_pk_mul_f32 v[118:119], v[172:173], v[118:119]
	s_nop 0
	v_cvt_pk_bf16_f32 v166, v118, v119
	v_lshlrev_b32_e32 v170, 16, v45
	v_and_b32_e32 v171, 0xffff0000, v45
	v_mul_f32_e32 v167, 0xbfb8aa3b, v170
	v_exp_f32_e32 v167, v167
	s_nop 0
	v_add_f32_e32 v167, 1.0, v167
	v_rcp_f32_e32 v172, v167
	v_mul_f32_e32 v167, 0xbfb8aa3b, v171
	v_exp_f32_e32 v167, v167
	s_nop 0
	v_add_f32_e32 v167, 1.0, v167
	v_rcp_f32_e32 v173, v167
	s_nop 1
	v_pk_mul_f32 v[172:173], v[172:173], v[170:171]
	s_nop 0
	v_pk_mul_f32 v[120:121], v[172:173], v[120:121]
	s_nop 0
	v_cvt_pk_bf16_f32 v167, v120, v121
	s_nop 0
	global_store_dwordx2 v[132:133], v[166:167], off offset:2240
	global_load_dwordx4 v[118:121], v[130:131], off offset:576
	s_waitcnt lgkmcnt(0)
	ds_read_b128 v[174:177], v103
	ds_read_b128 v[178:181], v103 offset:64
	ds_read_b128 v[182:185], v103 offset:128
	ds_read_b128 v[186:189], v103 offset:192
	ds_read_b128 v[190:193], v103 offset:256
	ds_read_b128 v[194:197], v103 offset:320
	ds_read_b128 v[198:201], v103 offset:384
	ds_read_b128 v[202:205], v103 offset:448
	v_mfma_f32_16x16x32_bf16 v[162:165], v[206:209], v[0:3], 0
	v_mfma_f32_16x16x32_bf16 v[162:165], v[210:213], v[4:7], v[162:165]
	v_mfma_f32_16x16x32_bf16 v[162:165], v[214:217], v[8:11], v[162:165]
	v_mfma_f32_16x16x32_bf16 v[162:165], v[218:221], v[12:15], v[162:165]
	v_mfma_f32_16x16x32_bf16 v[162:165], v[222:225], v[16:19], v[162:165]
	v_mfma_f32_16x16x32_bf16 v[162:165], v[226:229], v[20:23], v[162:165]
	v_mfma_f32_16x16x32_bf16 v[162:165], v[230:233], v[24:27], v[162:165]
	v_mfma_f32_16x16x32_bf16 v[162:165], v[234:237], v[28:31], v[162:165]
	s_waitcnt vmcnt(25)
	v_lshlrev_b32_e32 v170, 16, v46
	v_and_b32_e32 v171, 0xffff0000, v46
	v_mul_f32_e32 v166, 0xbfb8aa3b, v170
	v_exp_f32_e32 v166, v166
	s_nop 0
	v_add_f32_e32 v166, 1.0, v166
	v_rcp_f32_e32 v172, v166
	v_mul_f32_e32 v166, 0xbfb8aa3b, v171
	v_exp_f32_e32 v166, v166
	s_nop 0
	v_add_f32_e32 v166, 1.0, v166
	v_rcp_f32_e32 v173, v166
	s_waitcnt vmcnt(4)
	v_pk_mul_f32 v[122:123], v[122:123], v[162:163]
	v_pk_mul_f32 v[124:125], v[124:125], v[164:165]
	v_pk_mul_f32 v[172:173], v[172:173], v[170:171]
	s_nop 0
	v_pk_mul_f32 v[122:123], v[172:173], v[122:123]
	s_nop 0
	v_cvt_pk_bf16_f32 v166, v122, v123
	v_lshlrev_b32_e32 v170, 16, v47
	v_and_b32_e32 v171, 0xffff0000, v47
	v_mul_f32_e32 v167, 0xbfb8aa3b, v170
	v_exp_f32_e32 v167, v167
	s_nop 0
	v_add_f32_e32 v167, 1.0, v167
	v_rcp_f32_e32 v172, v167
	v_mul_f32_e32 v167, 0xbfb8aa3b, v171
	v_exp_f32_e32 v167, v167
	s_nop 0
	v_add_f32_e32 v167, 1.0, v167
	v_rcp_f32_e32 v173, v167
	s_nop 1
	v_pk_mul_f32 v[172:173], v[172:173], v[170:171]
	s_nop 0
	v_pk_mul_f32 v[124:125], v[172:173], v[124:125]
	s_nop 0
	v_cvt_pk_bf16_f32 v167, v124, v125
	s_nop 0
	global_store_dwordx2 v[132:133], v[166:167], off offset:2272
	global_load_dwordx4 v[122:125], v[130:131], off offset:640
	s_waitcnt lgkmcnt(0)
	ds_read_b128 v[206:209], v103 offset:8448
	ds_read_b128 v[210:213], v103 offset:8512
	ds_read_b128 v[214:217], v103 offset:8576
	ds_read_b128 v[218:221], v103 offset:8640
	ds_read_b128 v[222:225], v103 offset:8704
	ds_read_b128 v[226:229], v103 offset:8768
	ds_read_b128 v[230:233], v103 offset:8832
	ds_read_b128 v[234:237], v103 offset:8896
	v_mfma_f32_16x16x32_bf16 v[162:165], v[174:177], v[0:3], 0
	v_mfma_f32_16x16x32_bf16 v[162:165], v[178:181], v[4:7], v[162:165]
	v_mfma_f32_16x16x32_bf16 v[162:165], v[182:185], v[8:11], v[162:165]
	v_mfma_f32_16x16x32_bf16 v[162:165], v[186:189], v[12:15], v[162:165]
	v_mfma_f32_16x16x32_bf16 v[162:165], v[190:193], v[16:19], v[162:165]
	v_mfma_f32_16x16x32_bf16 v[162:165], v[194:197], v[20:23], v[162:165]
	v_mfma_f32_16x16x32_bf16 v[162:165], v[198:201], v[24:27], v[162:165]
	v_mfma_f32_16x16x32_bf16 v[162:165], v[202:205], v[28:31], v[162:165]
	s_waitcnt vmcnt(26)
	v_lshlrev_b32_e32 v170, 16, v48
	v_and_b32_e32 v171, 0xffff0000, v48
	v_mul_f32_e32 v166, 0xbfb8aa3b, v170
	v_exp_f32_e32 v166, v166
	s_nop 0
	v_add_f32_e32 v166, 1.0, v166
	v_rcp_f32_e32 v172, v166
	v_mul_f32_e32 v166, 0xbfb8aa3b, v171
	v_exp_f32_e32 v166, v166
	s_nop 0
	v_add_f32_e32 v166, 1.0, v166
	v_rcp_f32_e32 v173, v166
	s_waitcnt vmcnt(4)
	v_pk_mul_f32 v[126:127], v[126:127], v[162:163]
	v_pk_mul_f32 v[128:129], v[128:129], v[164:165]
	v_pk_mul_f32 v[172:173], v[172:173], v[170:171]
	s_nop 0
	v_pk_mul_f32 v[126:127], v[172:173], v[126:127]
	s_nop 0
	v_cvt_pk_bf16_f32 v166, v126, v127
	v_lshlrev_b32_e32 v170, 16, v49
	v_and_b32_e32 v171, 0xffff0000, v49
	v_mul_f32_e32 v167, 0xbfb8aa3b, v170
	v_exp_f32_e32 v167, v167
	s_nop 0
	v_add_f32_e32 v167, 1.0, v167
	v_rcp_f32_e32 v172, v167
	v_mul_f32_e32 v167, 0xbfb8aa3b, v171
	v_exp_f32_e32 v167, v167
	s_nop 0
	v_add_f32_e32 v167, 1.0, v167
	v_rcp_f32_e32 v173, v167
	s_nop 1
	v_pk_mul_f32 v[172:173], v[172:173], v[170:171]
	s_nop 0
	v_pk_mul_f32 v[128:129], v[172:173], v[128:129]
	s_nop 0
	v_cvt_pk_bf16_f32 v167, v128, v129
	s_nop 0
	global_store_dwordx2 v[132:133], v[166:167], off offset:2304
	global_load_dwordx4 v[126:129], v[130:131], off offset:704
	s_waitcnt lgkmcnt(0)
	ds_read_b128 v[174:177], v103 offset:16896
	ds_read_b128 v[178:181], v103 offset:16960
	ds_read_b128 v[182:185], v103 offset:17024
	ds_read_b128 v[186:189], v103 offset:17088
	ds_read_b128 v[190:193], v103 offset:17152
	ds_read_b128 v[194:197], v103 offset:17216
	ds_read_b128 v[198:201], v103 offset:17280
	ds_read_b128 v[202:205], v103 offset:17344
	v_mfma_f32_16x16x32_bf16 v[162:165], v[206:209], v[0:3], 0
	v_mfma_f32_16x16x32_bf16 v[162:165], v[210:213], v[4:7], v[162:165]
	v_mfma_f32_16x16x32_bf16 v[162:165], v[214:217], v[8:11], v[162:165]
	v_mfma_f32_16x16x32_bf16 v[162:165], v[218:221], v[12:15], v[162:165]
	v_mfma_f32_16x16x32_bf16 v[162:165], v[222:225], v[16:19], v[162:165]
	v_mfma_f32_16x16x32_bf16 v[162:165], v[226:229], v[20:23], v[162:165]
	v_mfma_f32_16x16x32_bf16 v[162:165], v[230:233], v[24:27], v[162:165]
	v_mfma_f32_16x16x32_bf16 v[162:165], v[234:237], v[28:31], v[162:165]
	s_waitcnt vmcnt(27)
	v_lshlrev_b32_e32 v170, 16, v50
	v_and_b32_e32 v171, 0xffff0000, v50
	v_mul_f32_e32 v166, 0xbfb8aa3b, v170
	v_exp_f32_e32 v166, v166
	s_nop 0
	v_add_f32_e32 v166, 1.0, v166
	v_rcp_f32_e32 v172, v166
	v_mul_f32_e32 v166, 0xbfb8aa3b, v171
	v_exp_f32_e32 v166, v166
	s_nop 0
	v_add_f32_e32 v166, 1.0, v166
	v_rcp_f32_e32 v173, v166
	s_waitcnt vmcnt(4)
	v_pk_mul_f32 v[118:119], v[118:119], v[162:163]
	v_pk_mul_f32 v[120:121], v[120:121], v[164:165]
	v_pk_mul_f32 v[172:173], v[172:173], v[170:171]
	s_nop 0
	v_pk_mul_f32 v[118:119], v[172:173], v[118:119]
	s_nop 0
	v_cvt_pk_bf16_f32 v166, v118, v119
	v_lshlrev_b32_e32 v170, 16, v51
	v_and_b32_e32 v171, 0xffff0000, v51
	v_mul_f32_e32 v167, 0xbfb8aa3b, v170
	v_exp_f32_e32 v167, v167
	s_nop 0
	v_add_f32_e32 v167, 1.0, v167
	v_rcp_f32_e32 v172, v167
	v_mul_f32_e32 v167, 0xbfb8aa3b, v171
	v_exp_f32_e32 v167, v167
	s_nop 0
	v_add_f32_e32 v167, 1.0, v167
	v_rcp_f32_e32 v173, v167
	s_nop 1
	v_pk_mul_f32 v[172:173], v[172:173], v[170:171]
	s_nop 0
	v_pk_mul_f32 v[120:121], v[172:173], v[120:121]
	s_nop 0
	v_cvt_pk_bf16_f32 v167, v120, v121
	s_nop 0
	global_store_dwordx2 v[132:133], v[166:167], off offset:2336
	global_load_dwordx4 v[118:121], v[130:131], off offset:768
	s_waitcnt lgkmcnt(0)
	ds_read_b128 v[206:209], v103 offset:25344
	ds_read_b128 v[210:213], v103 offset:25408
	ds_read_b128 v[214:217], v103 offset:25472
	ds_read_b128 v[218:221], v103 offset:25536
	ds_read_b128 v[222:225], v103 offset:25600
	ds_read_b128 v[226:229], v103 offset:25664
	ds_read_b128 v[230:233], v103 offset:25728
	ds_read_b128 v[234:237], v103 offset:25792
	v_mfma_f32_16x16x32_bf16 v[162:165], v[174:177], v[0:3], 0
	v_mfma_f32_16x16x32_bf16 v[162:165], v[178:181], v[4:7], v[162:165]
	v_mfma_f32_16x16x32_bf16 v[162:165], v[182:185], v[8:11], v[162:165]
	v_mfma_f32_16x16x32_bf16 v[162:165], v[186:189], v[12:15], v[162:165]
	v_mfma_f32_16x16x32_bf16 v[162:165], v[190:193], v[16:19], v[162:165]
	v_mfma_f32_16x16x32_bf16 v[162:165], v[194:197], v[20:23], v[162:165]
	v_mfma_f32_16x16x32_bf16 v[162:165], v[198:201], v[24:27], v[162:165]
	v_mfma_f32_16x16x32_bf16 v[162:165], v[202:205], v[28:31], v[162:165]
	s_waitcnt vmcnt(28)
	v_lshlrev_b32_e32 v170, 16, v52
	v_and_b32_e32 v171, 0xffff0000, v52
	v_mul_f32_e32 v166, 0xbfb8aa3b, v170
	v_exp_f32_e32 v166, v166
	s_nop 0
	v_add_f32_e32 v166, 1.0, v166
	v_rcp_f32_e32 v172, v166
	v_mul_f32_e32 v166, 0xbfb8aa3b, v171
	v_exp_f32_e32 v166, v166
	s_nop 0
	v_add_f32_e32 v166, 1.0, v166
	v_rcp_f32_e32 v173, v166
	s_waitcnt vmcnt(4)
	v_pk_mul_f32 v[122:123], v[122:123], v[162:163]
	v_pk_mul_f32 v[124:125], v[124:125], v[164:165]
	v_pk_mul_f32 v[172:173], v[172:173], v[170:171]
	s_nop 0
	v_pk_mul_f32 v[122:123], v[172:173], v[122:123]
	s_nop 0
	v_cvt_pk_bf16_f32 v166, v122, v123
	v_lshlrev_b32_e32 v170, 16, v53
	v_and_b32_e32 v171, 0xffff0000, v53
	v_mul_f32_e32 v167, 0xbfb8aa3b, v170
	v_exp_f32_e32 v167, v167
	s_nop 0
	v_add_f32_e32 v167, 1.0, v167
	v_rcp_f32_e32 v172, v167
	v_mul_f32_e32 v167, 0xbfb8aa3b, v171
	v_exp_f32_e32 v167, v167
	s_nop 0
	v_add_f32_e32 v167, 1.0, v167
	v_rcp_f32_e32 v173, v167
	s_nop 1
	v_pk_mul_f32 v[172:173], v[172:173], v[170:171]
	s_nop 0
	v_pk_mul_f32 v[124:125], v[172:173], v[124:125]
	s_nop 0
	v_cvt_pk_bf16_f32 v167, v124, v125
	s_nop 0
	global_store_dwordx2 v[132:133], v[166:167], off offset:2368
	global_load_dwordx4 v[122:125], v[130:131], off offset:832
	s_waitcnt lgkmcnt(0)
	ds_read_b128 v[174:177], v103 offset:33792
	ds_read_b128 v[178:181], v103 offset:33856
	ds_read_b128 v[182:185], v103 offset:33920
	ds_read_b128 v[186:189], v103 offset:33984
	ds_read_b128 v[190:193], v103 offset:34048
	ds_read_b128 v[194:197], v103 offset:34112
	ds_read_b128 v[198:201], v103 offset:34176
	ds_read_b128 v[202:205], v103 offset:34240
	v_mfma_f32_16x16x32_bf16 v[162:165], v[206:209], v[0:3], 0
	v_mfma_f32_16x16x32_bf16 v[162:165], v[210:213], v[4:7], v[162:165]
	v_mfma_f32_16x16x32_bf16 v[162:165], v[214:217], v[8:11], v[162:165]
	v_mfma_f32_16x16x32_bf16 v[162:165], v[218:221], v[12:15], v[162:165]
	v_mfma_f32_16x16x32_bf16 v[162:165], v[222:225], v[16:19], v[162:165]
	v_mfma_f32_16x16x32_bf16 v[162:165], v[226:229], v[20:23], v[162:165]
	v_mfma_f32_16x16x32_bf16 v[162:165], v[230:233], v[24:27], v[162:165]
	v_mfma_f32_16x16x32_bf16 v[162:165], v[234:237], v[28:31], v[162:165]
	s_waitcnt vmcnt(29)
	v_lshlrev_b32_e32 v170, 16, v54
	v_and_b32_e32 v171, 0xffff0000, v54
	v_mul_f32_e32 v166, 0xbfb8aa3b, v170
	v_exp_f32_e32 v166, v166
	s_nop 0
	v_add_f32_e32 v166, 1.0, v166
	v_rcp_f32_e32 v172, v166
	v_mul_f32_e32 v166, 0xbfb8aa3b, v171
	v_exp_f32_e32 v166, v166
	s_nop 0
	v_add_f32_e32 v166, 1.0, v166
	v_rcp_f32_e32 v173, v166
	s_waitcnt vmcnt(4)
	v_pk_mul_f32 v[126:127], v[126:127], v[162:163]
	v_pk_mul_f32 v[128:129], v[128:129], v[164:165]
	v_pk_mul_f32 v[172:173], v[172:173], v[170:171]
	s_nop 0
	v_pk_mul_f32 v[126:127], v[172:173], v[126:127]
	s_nop 0
	v_cvt_pk_bf16_f32 v166, v126, v127
	v_lshlrev_b32_e32 v170, 16, v55
	v_and_b32_e32 v171, 0xffff0000, v55
	v_mul_f32_e32 v167, 0xbfb8aa3b, v170
	v_exp_f32_e32 v167, v167
	s_nop 0
	v_add_f32_e32 v167, 1.0, v167
	v_rcp_f32_e32 v172, v167
	v_mul_f32_e32 v167, 0xbfb8aa3b, v171
	v_exp_f32_e32 v167, v167
	s_nop 0
	v_add_f32_e32 v167, 1.0, v167
	v_rcp_f32_e32 v173, v167
	s_nop 1
	v_pk_mul_f32 v[172:173], v[172:173], v[170:171]
	s_nop 0
	v_pk_mul_f32 v[128:129], v[172:173], v[128:129]
	s_nop 0
	v_cvt_pk_bf16_f32 v167, v128, v129
	s_nop 0
	global_store_dwordx2 v[132:133], v[166:167], off offset:2400
	global_load_dwordx4 v[126:129], v[130:131], off offset:896
	s_waitcnt lgkmcnt(0)
	ds_read_b128 v[206:209], v103 offset:42240
	ds_read_b128 v[210:213], v103 offset:42304
	ds_read_b128 v[214:217], v103 offset:42368
	ds_read_b128 v[218:221], v103 offset:42432
	ds_read_b128 v[222:225], v103 offset:42496
	ds_read_b128 v[226:229], v103 offset:42560
	ds_read_b128 v[230:233], v103 offset:42624
	ds_read_b128 v[234:237], v103 offset:42688
	v_mfma_f32_16x16x32_bf16 v[162:165], v[174:177], v[0:3], 0
	v_mfma_f32_16x16x32_bf16 v[162:165], v[178:181], v[4:7], v[162:165]
	v_mfma_f32_16x16x32_bf16 v[162:165], v[182:185], v[8:11], v[162:165]
	v_mfma_f32_16x16x32_bf16 v[162:165], v[186:189], v[12:15], v[162:165]
	v_mfma_f32_16x16x32_bf16 v[162:165], v[190:193], v[16:19], v[162:165]
	v_mfma_f32_16x16x32_bf16 v[162:165], v[194:197], v[20:23], v[162:165]
	v_mfma_f32_16x16x32_bf16 v[162:165], v[198:201], v[24:27], v[162:165]
	v_mfma_f32_16x16x32_bf16 v[162:165], v[202:205], v[28:31], v[162:165]
	s_waitcnt vmcnt(30)
	v_lshlrev_b32_e32 v170, 16, v56
	v_and_b32_e32 v171, 0xffff0000, v56
	v_mul_f32_e32 v166, 0xbfb8aa3b, v170
	v_exp_f32_e32 v166, v166
	s_nop 0
	v_add_f32_e32 v166, 1.0, v166
	v_rcp_f32_e32 v172, v166
	v_mul_f32_e32 v166, 0xbfb8aa3b, v171
	v_exp_f32_e32 v166, v166
	s_nop 0
	v_add_f32_e32 v166, 1.0, v166
	v_rcp_f32_e32 v173, v166
	s_waitcnt vmcnt(4)
	v_pk_mul_f32 v[118:119], v[118:119], v[162:163]
	v_pk_mul_f32 v[120:121], v[120:121], v[164:165]
	v_pk_mul_f32 v[172:173], v[172:173], v[170:171]
	s_nop 0
	v_pk_mul_f32 v[118:119], v[172:173], v[118:119]
	s_nop 0
	v_cvt_pk_bf16_f32 v166, v118, v119
	v_lshlrev_b32_e32 v170, 16, v57
	v_and_b32_e32 v171, 0xffff0000, v57
	v_mul_f32_e32 v167, 0xbfb8aa3b, v170
	v_exp_f32_e32 v167, v167
	s_nop 0
	v_add_f32_e32 v167, 1.0, v167
	v_rcp_f32_e32 v172, v167
	v_mul_f32_e32 v167, 0xbfb8aa3b, v171
	v_exp_f32_e32 v167, v167
	s_nop 0
	v_add_f32_e32 v167, 1.0, v167
	v_rcp_f32_e32 v173, v167
	s_nop 1
	v_pk_mul_f32 v[172:173], v[172:173], v[170:171]
	s_nop 0
	v_pk_mul_f32 v[120:121], v[172:173], v[120:121]
	s_nop 0
	v_cvt_pk_bf16_f32 v167, v120, v121
	s_nop 0
	global_store_dwordx2 v[132:133], v[166:167], off offset:2432
	global_load_dwordx4 v[118:121], v[130:131], off offset:960
	s_waitcnt lgkmcnt(0)
	ds_read_b128 v[174:177], v103 offset:50688
	ds_read_b128 v[178:181], v103 offset:50752
	ds_read_b128 v[182:185], v103 offset:50816
	ds_read_b128 v[186:189], v103 offset:50880
	ds_read_b128 v[190:193], v103 offset:50944
	ds_read_b128 v[194:197], v103 offset:51008
	ds_read_b128 v[198:201], v103 offset:51072
	ds_read_b128 v[202:205], v103 offset:51136
	v_mfma_f32_16x16x32_bf16 v[162:165], v[206:209], v[0:3], 0
	v_mfma_f32_16x16x32_bf16 v[162:165], v[210:213], v[4:7], v[162:165]
	v_mfma_f32_16x16x32_bf16 v[162:165], v[214:217], v[8:11], v[162:165]
	v_mfma_f32_16x16x32_bf16 v[162:165], v[218:221], v[12:15], v[162:165]
	v_mfma_f32_16x16x32_bf16 v[162:165], v[222:225], v[16:19], v[162:165]
	v_mfma_f32_16x16x32_bf16 v[162:165], v[226:229], v[20:23], v[162:165]
	v_mfma_f32_16x16x32_bf16 v[162:165], v[230:233], v[24:27], v[162:165]
	v_mfma_f32_16x16x32_bf16 v[162:165], v[234:237], v[28:31], v[162:165]
	s_waitcnt vmcnt(31)
	v_lshlrev_b32_e32 v170, 16, v58
	v_and_b32_e32 v171, 0xffff0000, v58
	v_mul_f32_e32 v166, 0xbfb8aa3b, v170
	v_exp_f32_e32 v166, v166
	s_nop 0
	v_add_f32_e32 v166, 1.0, v166
	v_rcp_f32_e32 v172, v166
	v_mul_f32_e32 v166, 0xbfb8aa3b, v171
	v_exp_f32_e32 v166, v166
	s_nop 0
	v_add_f32_e32 v166, 1.0, v166
	v_rcp_f32_e32 v173, v166
	s_waitcnt vmcnt(4)
	v_pk_mul_f32 v[122:123], v[122:123], v[162:163]
	v_pk_mul_f32 v[124:125], v[124:125], v[164:165]
	v_pk_mul_f32 v[172:173], v[172:173], v[170:171]
	s_nop 0
	v_pk_mul_f32 v[122:123], v[172:173], v[122:123]
	s_nop 0
	v_cvt_pk_bf16_f32 v166, v122, v123
	v_lshlrev_b32_e32 v170, 16, v59
	v_and_b32_e32 v171, 0xffff0000, v59
	v_mul_f32_e32 v167, 0xbfb8aa3b, v170
	v_exp_f32_e32 v167, v167
	s_nop 0
	v_add_f32_e32 v167, 1.0, v167
	v_rcp_f32_e32 v172, v167
	v_mul_f32_e32 v167, 0xbfb8aa3b, v171
	v_exp_f32_e32 v167, v167
	s_nop 0
	v_add_f32_e32 v167, 1.0, v167
	v_rcp_f32_e32 v173, v167
	s_nop 1
	v_pk_mul_f32 v[172:173], v[172:173], v[170:171]
	s_nop 0
	v_pk_mul_f32 v[124:125], v[172:173], v[124:125]
	s_nop 0
	v_cvt_pk_bf16_f32 v167, v124, v125
	s_nop 0
	global_store_dwordx2 v[132:133], v[166:167], off offset:2464
	s_waitcnt lgkmcnt(0)
	ds_read_b128 v[206:209], v103 offset:59136
	ds_read_b128 v[210:213], v103 offset:59200
	ds_read_b128 v[214:217], v103 offset:59264
	ds_read_b128 v[218:221], v103 offset:59328
	ds_read_b128 v[222:225], v103 offset:59392
	ds_read_b128 v[226:229], v103 offset:59456
	ds_read_b128 v[230:233], v103 offset:59520
	ds_read_b128 v[234:237], v103 offset:59584
	v_mfma_f32_16x16x32_bf16 v[162:165], v[174:177], v[0:3], 0
	v_mfma_f32_16x16x32_bf16 v[162:165], v[178:181], v[4:7], v[162:165]
	v_mfma_f32_16x16x32_bf16 v[162:165], v[182:185], v[8:11], v[162:165]
	v_mfma_f32_16x16x32_bf16 v[162:165], v[186:189], v[12:15], v[162:165]
	v_mfma_f32_16x16x32_bf16 v[162:165], v[190:193], v[16:19], v[162:165]
	v_mfma_f32_16x16x32_bf16 v[162:165], v[194:197], v[20:23], v[162:165]
	v_mfma_f32_16x16x32_bf16 v[162:165], v[198:201], v[24:27], v[162:165]
	v_mfma_f32_16x16x32_bf16 v[162:165], v[202:205], v[28:31], v[162:165]
	s_waitcnt vmcnt(31)
	v_lshlrev_b32_e32 v170, 16, v60
	v_and_b32_e32 v171, 0xffff0000, v60
	v_mul_f32_e32 v166, 0xbfb8aa3b, v170
	v_exp_f32_e32 v166, v166
	s_nop 0
	v_add_f32_e32 v166, 1.0, v166
	v_rcp_f32_e32 v172, v166
	v_mul_f32_e32 v166, 0xbfb8aa3b, v171
	v_exp_f32_e32 v166, v166
	s_nop 0
	v_add_f32_e32 v166, 1.0, v166
	v_rcp_f32_e32 v173, v166
	s_waitcnt vmcnt(3)
	v_pk_mul_f32 v[126:127], v[126:127], v[162:163]
	v_pk_mul_f32 v[128:129], v[128:129], v[164:165]
	v_pk_mul_f32 v[172:173], v[172:173], v[170:171]
	s_nop 0
	v_pk_mul_f32 v[126:127], v[172:173], v[126:127]
	s_nop 0
	v_cvt_pk_bf16_f32 v166, v126, v127
	v_lshlrev_b32_e32 v170, 16, v61
	v_and_b32_e32 v171, 0xffff0000, v61
	v_mul_f32_e32 v167, 0xbfb8aa3b, v170
	v_exp_f32_e32 v167, v167
	s_nop 0
	v_add_f32_e32 v167, 1.0, v167
	v_rcp_f32_e32 v172, v167
	v_mul_f32_e32 v167, 0xbfb8aa3b, v171
	v_exp_f32_e32 v167, v167
	s_nop 0
	v_add_f32_e32 v167, 1.0, v167
	v_rcp_f32_e32 v173, v167
	s_nop 1
	v_pk_mul_f32 v[172:173], v[172:173], v[170:171]
	s_nop 0
	v_pk_mul_f32 v[128:129], v[172:173], v[128:129]
	s_nop 0
	v_cvt_pk_bf16_f32 v167, v128, v129
	s_nop 0
	global_store_dwordx2 v[132:133], v[166:167], off offset:2496
	s_waitcnt lgkmcnt(0)
	v_mfma_f32_16x16x32_bf16 v[162:165], v[206:209], v[0:3], 0
	v_mfma_f32_16x16x32_bf16 v[162:165], v[210:213], v[4:7], v[162:165]
	v_mfma_f32_16x16x32_bf16 v[162:165], v[214:217], v[8:11], v[162:165]
	v_mfma_f32_16x16x32_bf16 v[162:165], v[218:221], v[12:15], v[162:165]
	v_mfma_f32_16x16x32_bf16 v[162:165], v[222:225], v[16:19], v[162:165]
	v_mfma_f32_16x16x32_bf16 v[162:165], v[226:229], v[20:23], v[162:165]
	v_mfma_f32_16x16x32_bf16 v[162:165], v[230:233], v[24:27], v[162:165]
	v_mfma_f32_16x16x32_bf16 v[162:165], v[234:237], v[28:31], v[162:165]
	s_waitcnt vmcnt(31)
	v_lshlrev_b32_e32 v170, 16, v62
	v_and_b32_e32 v171, 0xffff0000, v62
	v_mul_f32_e32 v166, 0xbfb8aa3b, v170
	v_exp_f32_e32 v166, v166
	s_nop 0
	v_add_f32_e32 v166, 1.0, v166
	v_rcp_f32_e32 v172, v166
	v_mul_f32_e32 v166, 0xbfb8aa3b, v171
	v_exp_f32_e32 v166, v166
	s_nop 0
	v_add_f32_e32 v166, 1.0, v166
	v_rcp_f32_e32 v173, v166
	s_waitcnt vmcnt(2)
	v_pk_mul_f32 v[118:119], v[118:119], v[162:163]
	v_pk_mul_f32 v[120:121], v[120:121], v[164:165]
	v_pk_mul_f32 v[172:173], v[172:173], v[170:171]
	s_nop 0
	v_pk_mul_f32 v[118:119], v[172:173], v[118:119]
	s_nop 0
	v_cvt_pk_bf16_f32 v166, v118, v119
	v_lshlrev_b32_e32 v170, 16, v63
	v_and_b32_e32 v171, 0xffff0000, v63
	v_mul_f32_e32 v167, 0xbfb8aa3b, v170
	v_exp_f32_e32 v167, v167
	s_nop 0
	v_add_f32_e32 v167, 1.0, v167
	v_rcp_f32_e32 v172, v167
	v_mul_f32_e32 v167, 0xbfb8aa3b, v171
	v_exp_f32_e32 v167, v167
	s_nop 0
	v_add_f32_e32 v167, 1.0, v167
	v_rcp_f32_e32 v173, v167
	s_nop 1
	v_pk_mul_f32 v[172:173], v[172:173], v[170:171]
	s_nop 0
	v_pk_mul_f32 v[120:121], v[172:173], v[120:121]
	s_nop 0
	v_cvt_pk_bf16_f32 v167, v120, v121
	s_nop 0
	global_store_dwordx2 v[132:133], v[166:167], off offset:2528
	s_cmp_lg_u32 s0, 0
	s_cbranch_scc1 .LBB0_554
	ds_read_b128 v[0:3], v160
	ds_read_b128 v[4:7], v160 offset:64
	ds_read_b128 v[8:11], v160 offset:128
	ds_read_b128 v[12:15], v160 offset:192
	ds_read_b128 v[16:19], v160 offset:256
	ds_read_b128 v[20:23], v160 offset:320
	ds_read_b128 v[24:27], v160 offset:384
	ds_read_b128 v[28:31], v160 offset:448
	ds_read_b128 v[32:35], v161
	ds_read_b128 v[36:39], v161 offset:64
	ds_read_b128 v[40:43], v161 offset:128
	ds_read_b128 v[44:47], v161 offset:192
	ds_read_b128 v[48:51], v161 offset:256
	ds_read_b128 v[52:55], v161 offset:320
	ds_read_b128 v[56:59], v161 offset:384
	ds_read_b128 v[60:63], v161 offset:448
	v_add_u32_e32 v110, v104, v141
	v_add_u32_e32 v112, v104, v142
	s_lshl_b64 s[0:1], s[8:9], 14
	v_ashrrev_i32_e32 v111, 31, v110
	v_ashrrev_i32_e32 v113, 31, v112
	v_lshl_add_u64 v[106:107], v[100:101], 0, s[0:1]
	v_lshl_add_u64 v[108:109], v[110:111], 2, s[60:61]
	v_lshl_add_u64 v[104:105], v[112:113], 2, s[60:61]
	s_mov_b32 s0, 0
	s_mov_b64 s[8:9], -1
	v_lshlrev_b64 v[110:111], 1, v[110:111]
	v_lshlrev_b64 v[112:113], 1, v[112:113]
